# GEMM main loops: loop counter and exit test moved ahead of the loop-back barrier (FF1, G_in, FF2, G_out)
# baseline (speedup 1.0000x reference)
.LBB0_67:
	s_add_i32 s20, s20, 2
	s_add_u32 s56, s56, 0x100
	s_addc_u32 s57, s57, 0
	s_cmp_gt_u32 s20, 13
	s_barrier
	s_cbranch_scc1 .LBB0_72

.LBB0_338:
	s_add_u32 s24, s20, 0xfffc0080
	s_addc_u32 s25, s21, -1
	s_add_i32 s72, 0, 0x10000
	s_cmp_eq_u32 s74, 12
	s_cselect_b32 s39, s3, s25
	s_cselect_b32 s38, s35, s24
	s_cselect_b32 s25, s43, s69
	s_cselect_b32 s24, s45, s68
	s_add_i32 s75, 0, 0x14000
	v_add_u32_e32 v156, s72, v145
	v_add_u32_e32 v172, s75, v145
	ds_read_b128 v[140:143], v156
	ds_read_b128 v[148:151], v156 offset:1024
	ds_read_b128 v[152:155], v156 offset:2048
	ds_read_b128 v[156:159], v156 offset:3072
	ds_read_b128 v[160:163], v172
	ds_read_b128 v[164:167], v172 offset:1024
	ds_read_b128 v[168:171], v172 offset:2048
	ds_read_b128 v[172:175], v172 offset:3072
	v_lshl_add_u64 v[198:199], s[20:21], 0, v[138:139]
	s_add_i32 m0, s7, 0xc000
	ds_read_b128 v[176:179], v147
	ds_read_b128 v[180:183], v147 offset:1024
	ds_read_b128 v[184:187], v147 offset:2048
	ds_read_b128 v[188:191], v147 offset:3072
	ds_read_b128 v[192:195], v147 offset:4096
	ds_read_b128 v[206:209], v147 offset:5120
	ds_read_b128 v[210:213], v147 offset:6144
	ds_read_b128 v[214:217], v147 offset:7168
	global_load_lds_dwordx4 v[198:199], off
	v_lshl_add_u64 v[198:199], s[20:21], 0, v[136:137]
	s_add_i32 m0, s7, 0xe000
	s_nop 0
	global_load_lds_dwordx4 v[198:199], off
	s_waitcnt vmcnt(8)
	s_waitcnt lgkmcnt(0)
	s_barrier
	s_setprio 1
	s_waitcnt lgkmcnt(0)
	v_mfma_f32_16x16x32_bf16 v[126:129], v[140:143], v[176:179], v[126:129]
	v_mfma_f32_16x16x32_bf16 v[122:125], v[152:155], v[176:179], v[122:125]
	v_mfma_f32_16x16x32_bf16 v[110:113], v[140:143], v[184:187], v[110:113]
	v_mfma_f32_16x16x32_bf16 v[106:109], v[152:155], v[184:187], v[106:109]
	v_mfma_f32_16x16x32_bf16 v[94:97], v[140:143], v[192:195], v[94:97]
	v_mfma_f32_16x16x32_bf16 v[90:93], v[152:155], v[192:195], v[90:93]
	v_mfma_f32_16x16x32_bf16 v[76:79], v[140:143], v[210:213], v[76:79]
	v_mfma_f32_16x16x32_bf16 v[72:75], v[152:155], v[210:213], v[72:75]
	v_mfma_f32_16x16x32_bf16 v[126:129], v[148:151], v[180:183], v[126:129]
	v_mfma_f32_16x16x32_bf16 v[122:125], v[156:159], v[180:183], v[122:125]
	v_mfma_f32_16x16x32_bf16 v[110:113], v[148:151], v[188:191], v[110:113]
	v_mfma_f32_16x16x32_bf16 v[106:109], v[156:159], v[188:191], v[106:109]
	v_mfma_f32_16x16x32_bf16 v[94:97], v[148:151], v[206:209], v[94:97]
	v_mfma_f32_16x16x32_bf16 v[90:93], v[156:159], v[206:209], v[90:93]
	v_mfma_f32_16x16x32_bf16 v[76:79], v[148:151], v[214:217], v[76:79]
	v_mfma_f32_16x16x32_bf16 v[72:75], v[156:159], v[214:217], v[72:75]
	s_setprio 0
	s_setprio 1
	v_mfma_f32_16x16x32_bf16 v[118:121], v[160:163], v[176:179], v[118:121]
	v_mfma_f32_16x16x32_bf16 v[114:117], v[168:171], v[176:179], v[114:117]
	v_mfma_f32_16x16x32_bf16 v[102:105], v[160:163], v[184:187], v[102:105]
	v_mfma_f32_16x16x32_bf16 v[98:101], v[168:171], v[184:187], v[98:101]
	v_mfma_f32_16x16x32_bf16 v[86:89], v[160:163], v[192:195], v[86:89]
	v_mfma_f32_16x16x32_bf16 v[82:85], v[168:171], v[192:195], v[82:85]
	v_mfma_f32_16x16x32_bf16 v[68:71], v[160:163], v[210:213], v[68:71]
	v_mfma_f32_16x16x32_bf16 v[64:67], v[168:171], v[210:213], v[64:67]
	v_mfma_f32_16x16x32_bf16 v[118:121], v[164:167], v[180:183], v[118:121]
	v_mfma_f32_16x16x32_bf16 v[114:117], v[172:175], v[180:183], v[114:117]
	v_mfma_f32_16x16x32_bf16 v[102:105], v[164:167], v[188:191], v[102:105]
	v_mfma_f32_16x16x32_bf16 v[98:101], v[172:175], v[188:191], v[98:101]
	v_mfma_f32_16x16x32_bf16 v[86:89], v[164:167], v[206:209], v[86:89]
	v_mfma_f32_16x16x32_bf16 v[82:85], v[172:175], v[206:209], v[82:85]
	v_mfma_f32_16x16x32_bf16 v[68:71], v[164:167], v[214:217], v[68:71]
	v_mfma_f32_16x16x32_bf16 v[64:67], v[172:175], v[214:217], v[64:67]
	s_setprio 0
	s_barrier
	s_add_i32 s72, s72, s55
	v_lshl_add_u64 v[198:199], s[24:25], 0, v[80:81]
	s_mov_b32 m0, s72
	ds_read_b128 v[176:179], v147 offset:16384
	ds_read_b128 v[180:183], v147 offset:17408
	ds_read_b128 v[184:187], v147 offset:18432
	ds_read_b128 v[188:191], v147 offset:19456
	ds_read_b128 v[192:195], v147 offset:20480
	ds_read_b128 v[206:209], v147 offset:21504
	ds_read_b128 v[210:213], v147 offset:22528
	ds_read_b128 v[214:217], v147 offset:23552
	global_load_lds_dwordx4 v[198:199], off
	s_add_i32 m0, s72, 0x2000
	s_add_u32 s76, s24, 0x40000
	v_lshl_add_u64 v[200:201], s[24:25], 0, v[134:135]
	s_addc_u32 s77, s25, 0
	s_add_i32 s72, s75, s55
	global_load_lds_dwordx4 v[200:201], off
	v_lshl_add_u64 v[202:203], s[76:77], 0, v[80:81]
	s_mov_b32 m0, s72
	v_lshl_add_u64 v[218:219], s[38:39], 0, v[132:133]
	global_load_lds_dwordx4 v[202:203], off
	v_lshl_add_u64 v[202:203], s[76:77], 0, v[134:135]
	s_add_i32 m0, s72, 0x2000
	s_nop 0
	global_load_lds_dwordx4 v[202:203], off
	v_lshl_add_u64 v[202:203], s[38:39], 0, v[130:131]
	s_mov_b32 m0, s7
	s_nop 0
	global_load_lds_dwordx4 v[202:203], off
	s_mov_b32 m0, s56
	s_nop 0
	global_load_lds_dwordx4 v[218:219], off
	s_waitcnt vmcnt(8)
	s_waitcnt lgkmcnt(0)
	s_barrier
	s_setprio 1
	s_waitcnt lgkmcnt(0)
	v_mfma_f32_16x16x32_bf16 v[60:63], v[140:143], v[176:179], v[60:63]
	v_mfma_f32_16x16x32_bf16 v[56:59], v[152:155], v[176:179], v[56:59]
	v_mfma_f32_16x16x32_bf16 v[44:47], v[140:143], v[184:187], v[44:47]
	v_mfma_f32_16x16x32_bf16 v[40:43], v[152:155], v[184:187], v[40:43]
	v_mfma_f32_16x16x32_bf16 v[28:31], v[140:143], v[192:195], v[28:31]
	v_mfma_f32_16x16x32_bf16 v[24:27], v[152:155], v[192:195], v[24:27]
	v_mfma_f32_16x16x32_bf16 v[12:15], v[140:143], v[210:213], v[12:15]
	v_mfma_f32_16x16x32_bf16 v[8:11], v[152:155], v[210:213], v[8:11]
	v_mfma_f32_16x16x32_bf16 v[60:63], v[148:151], v[180:183], v[60:63]
	v_mfma_f32_16x16x32_bf16 v[56:59], v[156:159], v[180:183], v[56:59]
	v_mfma_f32_16x16x32_bf16 v[44:47], v[148:151], v[188:191], v[44:47]
	v_mfma_f32_16x16x32_bf16 v[40:43], v[156:159], v[188:191], v[40:43]
	v_mfma_f32_16x16x32_bf16 v[28:31], v[148:151], v[206:209], v[28:31]
	v_mfma_f32_16x16x32_bf16 v[24:27], v[156:159], v[206:209], v[24:27]
	v_mfma_f32_16x16x32_bf16 v[12:15], v[148:151], v[214:217], v[12:15]
	v_mfma_f32_16x16x32_bf16 v[8:11], v[156:159], v[214:217], v[8:11]
	s_setprio 0
	s_setprio 1
	v_mfma_f32_16x16x32_bf16 v[52:55], v[160:163], v[176:179], v[52:55]
	v_mfma_f32_16x16x32_bf16 v[48:51], v[168:171], v[176:179], v[48:51]
	v_mfma_f32_16x16x32_bf16 v[36:39], v[160:163], v[184:187], v[36:39]
	v_mfma_f32_16x16x32_bf16 v[32:35], v[168:171], v[184:187], v[32:35]
	v_mfma_f32_16x16x32_bf16 v[20:23], v[160:163], v[192:195], v[20:23]
	v_mfma_f32_16x16x32_bf16 v[16:19], v[168:171], v[192:195], v[16:19]
	v_mfma_f32_16x16x32_bf16 v[4:7], v[160:163], v[210:213], v[4:7]
	v_mfma_f32_16x16x32_bf16 v[0:3], v[168:171], v[210:213], v[0:3]
	v_mfma_f32_16x16x32_bf16 v[52:55], v[164:167], v[180:183], v[52:55]
	v_mfma_f32_16x16x32_bf16 v[48:51], v[172:175], v[180:183], v[48:51]
	v_mfma_f32_16x16x32_bf16 v[36:39], v[164:167], v[188:191], v[36:39]
	v_mfma_f32_16x16x32_bf16 v[32:35], v[172:175], v[188:191], v[32:35]
	v_mfma_f32_16x16x32_bf16 v[20:23], v[164:167], v[206:209], v[20:23]
	v_mfma_f32_16x16x32_bf16 v[16:19], v[172:175], v[206:209], v[16:19]
	v_mfma_f32_16x16x32_bf16 v[4:7], v[164:167], v[214:217], v[4:7]
	v_mfma_f32_16x16x32_bf16 v[0:3], v[172:175], v[214:217], v[0:3]
	s_setprio 0
	s_barrier
	s_add_i32 s72, 0, 0x18000
	s_add_i32 s75, 0, 0x1c000
	v_add_u32_e32 v156, s72, v145
	v_add_u32_e32 v172, s75, v145
	ds_read_b128 v[140:143], v156
	ds_read_b128 v[148:151], v156 offset:1024
	ds_read_b128 v[152:155], v156 offset:2048
	ds_read_b128 v[156:159], v156 offset:3072
	ds_read_b128 v[160:163], v172
	ds_read_b128 v[164:167], v172 offset:1024
	ds_read_b128 v[168:171], v172 offset:2048
	ds_read_b128 v[172:175], v172 offset:3072
	s_add_u32 s38, s38, 0x40000
	s_addc_u32 s39, s39, 0
	s_mov_b32 m0, s57
	v_lshl_add_u64 v[220:221], s[38:39], 0, v[130:131]
	ds_read_b128 v[176:179], v147 offset:32768
	ds_read_b128 v[180:183], v147 offset:33792
	ds_read_b128 v[184:187], v147 offset:34816
	ds_read_b128 v[188:191], v147 offset:35840
	ds_read_b128 v[192:195], v147 offset:36864
	ds_read_b128 v[206:209], v147 offset:37888
	ds_read_b128 v[210:213], v147 offset:38912
	ds_read_b128 v[214:217], v147 offset:39936
	global_load_lds_dwordx4 v[220:221], off
	v_lshl_add_u64 v[220:221], s[38:39], 0, v[132:133]
	s_mov_b32 m0, s62
	s_nop 0
	global_load_lds_dwordx4 v[220:221], off
	s_waitcnt vmcnt(8)
	s_waitcnt lgkmcnt(0)
	s_barrier
	s_setprio 1
	s_waitcnt lgkmcnt(0)
	v_mfma_f32_16x16x32_bf16 v[126:129], v[140:143], v[176:179], v[126:129]
	v_mfma_f32_16x16x32_bf16 v[122:125], v[152:155], v[176:179], v[122:125]
	v_mfma_f32_16x16x32_bf16 v[110:113], v[140:143], v[184:187], v[110:113]
	v_mfma_f32_16x16x32_bf16 v[106:109], v[152:155], v[184:187], v[106:109]
	v_mfma_f32_16x16x32_bf16 v[94:97], v[140:143], v[192:195], v[94:97]
	v_mfma_f32_16x16x32_bf16 v[90:93], v[152:155], v[192:195], v[90:93]
	v_mfma_f32_16x16x32_bf16 v[76:79], v[140:143], v[210:213], v[76:79]
	v_mfma_f32_16x16x32_bf16 v[72:75], v[152:155], v[210:213], v[72:75]
	v_mfma_f32_16x16x32_bf16 v[126:129], v[148:151], v[180:183], v[126:129]
	v_mfma_f32_16x16x32_bf16 v[122:125], v[156:159], v[180:183], v[122:125]
	v_mfma_f32_16x16x32_bf16 v[110:113], v[148:151], v[188:191], v[110:113]
	v_mfma_f32_16x16x32_bf16 v[106:109], v[156:159], v[188:191], v[106:109]
	v_mfma_f32_16x16x32_bf16 v[94:97], v[148:151], v[206:209], v[94:97]
	v_mfma_f32_16x16x32_bf16 v[90:93], v[156:159], v[206:209], v[90:93]
	v_mfma_f32_16x16x32_bf16 v[76:79], v[148:151], v[214:217], v[76:79]
	v_mfma_f32_16x16x32_bf16 v[72:75], v[156:159], v[214:217], v[72:75]
	s_setprio 0
	s_setprio 1
	v_mfma_f32_16x16x32_bf16 v[118:121], v[160:163], v[176:179], v[118:121]
	v_mfma_f32_16x16x32_bf16 v[114:117], v[168:171], v[176:179], v[114:117]
	v_mfma_f32_16x16x32_bf16 v[102:105], v[160:163], v[184:187], v[102:105]
	v_mfma_f32_16x16x32_bf16 v[98:101], v[168:171], v[184:187], v[98:101]
	v_mfma_f32_16x16x32_bf16 v[86:89], v[160:163], v[192:195], v[86:89]
	v_mfma_f32_16x16x32_bf16 v[82:85], v[168:171], v[192:195], v[82:85]
	v_mfma_f32_16x16x32_bf16 v[68:71], v[160:163], v[210:213], v[68:71]
	v_mfma_f32_16x16x32_bf16 v[64:67], v[168:171], v[210:213], v[64:67]
	v_mfma_f32_16x16x32_bf16 v[118:121], v[164:167], v[180:183], v[118:121]
	v_mfma_f32_16x16x32_bf16 v[114:117], v[172:175], v[180:183], v[114:117]
	v_mfma_f32_16x16x32_bf16 v[102:105], v[164:167], v[188:191], v[102:105]
	v_mfma_f32_16x16x32_bf16 v[98:101], v[172:175], v[188:191], v[98:101]
	v_mfma_f32_16x16x32_bf16 v[86:89], v[164:167], v[206:209], v[86:89]
	v_mfma_f32_16x16x32_bf16 v[82:85], v[172:175], v[206:209], v[82:85]
	v_mfma_f32_16x16x32_bf16 v[68:71], v[164:167], v[214:217], v[68:71]
	v_mfma_f32_16x16x32_bf16 v[64:67], v[172:175], v[214:217], v[64:67]
	s_setprio 0
	s_barrier
	s_add_i32 s38, s72, s55
	v_lshl_add_u64 v[198:199], v[198:199], 0, s[18:19]
	s_mov_b32 m0, s38
	ds_read_b128 v[176:179], v147 offset:49152
	ds_read_b128 v[180:183], v147 offset:50176
	ds_read_b128 v[184:187], v147 offset:51200
	ds_read_b128 v[188:191], v147 offset:52224
	ds_read_b128 v[192:195], v147 offset:53248
	ds_read_b128 v[206:209], v147 offset:54272
	ds_read_b128 v[210:213], v147 offset:55296
	ds_read_b128 v[214:217], v147 offset:56320
	global_load_lds_dwordx4 v[198:199], off
	s_add_i32 m0, s38, 0x2000
	s_add_u32 s24, s24, 0x40080
	v_lshl_add_u64 v[198:199], v[200:201], 0, s[18:19]
	s_addc_u32 s25, s25, 0
	s_add_i32 s38, s75, s55
	global_load_lds_dwordx4 v[198:199], off
	v_lshl_add_u64 v[198:199], s[24:25], 0, v[80:81]
	s_mov_b32 m0, s38
	s_nop 0
	global_load_lds_dwordx4 v[198:199], off
	v_lshl_add_u64 v[198:199], s[24:25], 0, v[134:135]
	s_add_i32 m0, s38, 0x2000
	s_nop 0
	global_load_lds_dwordx4 v[198:199], off
	v_lshl_add_u64 v[198:199], v[202:203], 0, s[18:19]
	s_mov_b32 m0, s63
	s_nop 0
	global_load_lds_dwordx4 v[198:199], off
	v_lshl_add_u64 v[198:199], v[218:219], 0, s[18:19]
	s_mov_b32 m0, s64
	s_nop 0
	global_load_lds_dwordx4 v[198:199], off
	s_waitcnt vmcnt(8)
	s_waitcnt lgkmcnt(0)
	s_barrier
	s_setprio 1
	s_waitcnt lgkmcnt(0)
	v_mfma_f32_16x16x32_bf16 v[60:63], v[140:143], v[176:179], v[60:63]
	v_mfma_f32_16x16x32_bf16 v[56:59], v[152:155], v[176:179], v[56:59]
	v_mfma_f32_16x16x32_bf16 v[44:47], v[140:143], v[184:187], v[44:47]
	v_mfma_f32_16x16x32_bf16 v[40:43], v[152:155], v[184:187], v[40:43]
	v_mfma_f32_16x16x32_bf16 v[28:31], v[140:143], v[192:195], v[28:31]
	v_mfma_f32_16x16x32_bf16 v[24:27], v[152:155], v[192:195], v[24:27]
	v_mfma_f32_16x16x32_bf16 v[12:15], v[140:143], v[210:213], v[12:15]
	v_mfma_f32_16x16x32_bf16 v[8:11], v[152:155], v[210:213], v[8:11]
	v_mfma_f32_16x16x32_bf16 v[60:63], v[148:151], v[180:183], v[60:63]
	v_mfma_f32_16x16x32_bf16 v[56:59], v[156:159], v[180:183], v[56:59]
	v_mfma_f32_16x16x32_bf16 v[44:47], v[148:151], v[188:191], v[44:47]
	v_mfma_f32_16x16x32_bf16 v[40:43], v[156:159], v[188:191], v[40:43]
	v_mfma_f32_16x16x32_bf16 v[28:31], v[148:151], v[206:209], v[28:31]
	v_mfma_f32_16x16x32_bf16 v[24:27], v[156:159], v[206:209], v[24:27]
	v_mfma_f32_16x16x32_bf16 v[12:15], v[148:151], v[214:217], v[12:15]
	v_mfma_f32_16x16x32_bf16 v[8:11], v[156:159], v[214:217], v[8:11]
	s_setprio 0
	s_setprio 1
	v_mfma_f32_16x16x32_bf16 v[52:55], v[160:163], v[176:179], v[52:55]
	v_mfma_f32_16x16x32_bf16 v[48:51], v[168:171], v[176:179], v[48:51]
	v_mfma_f32_16x16x32_bf16 v[36:39], v[160:163], v[184:187], v[36:39]
	v_mfma_f32_16x16x32_bf16 v[32:35], v[168:171], v[184:187], v[32:35]
	v_mfma_f32_16x16x32_bf16 v[20:23], v[160:163], v[192:195], v[20:23]
	v_mfma_f32_16x16x32_bf16 v[16:19], v[168:171], v[192:195], v[16:19]
	v_mfma_f32_16x16x32_bf16 v[4:7], v[160:163], v[210:213], v[4:7]
	v_mfma_f32_16x16x32_bf16 v[0:3], v[168:171], v[210:213], v[0:3]
	v_mfma_f32_16x16x32_bf16 v[52:55], v[164:167], v[180:183], v[52:55]
	v_mfma_f32_16x16x32_bf16 v[48:51], v[172:175], v[180:183], v[48:51]
	v_mfma_f32_16x16x32_bf16 v[36:39], v[164:167], v[188:191], v[36:39]
	v_mfma_f32_16x16x32_bf16 v[32:35], v[172:175], v[188:191], v[32:35]
	v_mfma_f32_16x16x32_bf16 v[20:23], v[164:167], v[206:209], v[20:23]
	v_mfma_f32_16x16x32_bf16 v[16:19], v[172:175], v[206:209], v[16:19]
	v_mfma_f32_16x16x32_bf16 v[4:7], v[164:167], v[214:217], v[4:7]
	v_mfma_f32_16x16x32_bf16 v[0:3], v[172:175], v[214:217], v[0:3]
	s_setprio 0
	s_add_i32 s74, s74, 2
	s_add_u32 s68, s68, 0x100
	s_addc_u32 s69, s69, 0
	s_add_u32 s20, s20, 0x100
	s_addc_u32 s21, s21, 0
	s_cmp_gt_u32 s74, 13
	s_barrier
	s_cbranch_scc0 .LBB0_338
	s_and_b64 vcc, exec, s[40:41]
	s_cbranch_vccz .LBB0_341
	s_barrier

.LBB0_606:
	s_add_i32 s97, s97, 2
	s_add_u32 s52, s52, 0x10000
	s_addc_u32 s53, s53, 0
	s_cmp_gt_u32 s97, 61
	s_barrier
	s_cbranch_scc1 .LBB0_611

.LBB0_651:
	s_add_u32 s40, s38, 0xfffc0080
	s_addc_u32 s41, s39, -1
	s_add_i32 s73, 0, 0x10000
	s_cmp_eq_u32 s72, 12
	s_cselect_b32 s43, s9, s41
	s_cselect_b32 s42, s25, s40
	s_cselect_b32 s41, s7, s69
	s_cselect_b32 s40, s67, s68
	s_add_i32 s76, 0, 0x14000
	v_add_u32_e32 v172, s73, v158
	v_add_u32_e32 v188, s76, v158
	ds_read_b128 v[160:163], v172
	ds_read_b128 v[164:167], v172 offset:1024
	ds_read_b128 v[168:171], v172 offset:2048
	ds_read_b128 v[172:175], v172 offset:3072
	ds_read_b128 v[176:179], v188
	ds_read_b128 v[180:183], v188 offset:1024
	ds_read_b128 v[184:187], v188 offset:2048
	ds_read_b128 v[188:191], v188 offset:3072
	v_lshl_add_u64 v[198:199], s[38:39], 0, v[156:157]
	s_add_i32 m0, s51, 0xc000
	ds_read_b128 v[192:195], v159
	ds_read_b128 v[206:209], v159 offset:1024
	ds_read_b128 v[210:213], v159 offset:2048
	ds_read_b128 v[214:217], v159 offset:3072
	ds_read_b128 v[218:221], v159 offset:4096
	ds_read_b128 v[222:225], v159 offset:5120
	ds_read_b128 v[240:243], v159 offset:6144
	ds_read_b128 v[244:247], v159 offset:7168
	global_load_lds_dwordx4 v[198:199], off
	v_lshl_add_u64 v[198:199], s[38:39], 0, v[154:155]
	s_add_i32 m0, s51, 0xe000
	s_nop 0
	global_load_lds_dwordx4 v[198:199], off
	s_waitcnt vmcnt(8)
	s_waitcnt lgkmcnt(0)
	s_barrier
	s_setprio 1
	s_waitcnt lgkmcnt(0)
	v_mfma_f32_16x16x32_bf16 v[126:129], v[160:163], v[192:195], v[126:129]
	v_mfma_f32_16x16x32_bf16 v[122:125], v[168:171], v[192:195], v[122:125]
	v_mfma_f32_16x16x32_bf16 v[110:113], v[160:163], v[210:213], v[110:113]
	v_mfma_f32_16x16x32_bf16 v[106:109], v[168:171], v[210:213], v[106:109]
	v_mfma_f32_16x16x32_bf16 v[94:97], v[160:163], v[218:221], v[94:97]
	v_mfma_f32_16x16x32_bf16 v[90:93], v[168:171], v[218:221], v[90:93]
	v_mfma_f32_16x16x32_bf16 v[76:79], v[160:163], v[240:243], v[76:79]
	v_mfma_f32_16x16x32_bf16 v[72:75], v[168:171], v[240:243], v[72:75]
	v_mfma_f32_16x16x32_bf16 v[126:129], v[164:167], v[206:209], v[126:129]
	v_mfma_f32_16x16x32_bf16 v[122:125], v[172:175], v[206:209], v[122:125]
	v_mfma_f32_16x16x32_bf16 v[110:113], v[164:167], v[214:217], v[110:113]
	v_mfma_f32_16x16x32_bf16 v[106:109], v[172:175], v[214:217], v[106:109]
	v_mfma_f32_16x16x32_bf16 v[94:97], v[164:167], v[222:225], v[94:97]
	v_mfma_f32_16x16x32_bf16 v[90:93], v[172:175], v[222:225], v[90:93]
	v_mfma_f32_16x16x32_bf16 v[76:79], v[164:167], v[244:247], v[76:79]
	v_mfma_f32_16x16x32_bf16 v[72:75], v[172:175], v[244:247], v[72:75]
	s_setprio 0
	s_setprio 1
	v_mfma_f32_16x16x32_bf16 v[118:121], v[176:179], v[192:195], v[118:121]
	v_mfma_f32_16x16x32_bf16 v[114:117], v[184:187], v[192:195], v[114:117]
	v_mfma_f32_16x16x32_bf16 v[102:105], v[176:179], v[210:213], v[102:105]
	v_mfma_f32_16x16x32_bf16 v[98:101], v[184:187], v[210:213], v[98:101]
	v_mfma_f32_16x16x32_bf16 v[86:89], v[176:179], v[218:221], v[86:89]
	v_mfma_f32_16x16x32_bf16 v[82:85], v[184:187], v[218:221], v[82:85]
	v_mfma_f32_16x16x32_bf16 v[68:71], v[176:179], v[240:243], v[68:71]
	v_mfma_f32_16x16x32_bf16 v[64:67], v[184:187], v[240:243], v[64:67]
	v_mfma_f32_16x16x32_bf16 v[118:121], v[180:183], v[206:209], v[118:121]
	v_mfma_f32_16x16x32_bf16 v[114:117], v[188:191], v[206:209], v[114:117]
	v_mfma_f32_16x16x32_bf16 v[102:105], v[180:183], v[214:217], v[102:105]
	v_mfma_f32_16x16x32_bf16 v[98:101], v[188:191], v[214:217], v[98:101]
	v_mfma_f32_16x16x32_bf16 v[86:89], v[180:183], v[222:225], v[86:89]
	v_mfma_f32_16x16x32_bf16 v[82:85], v[188:191], v[222:225], v[82:85]
	v_mfma_f32_16x16x32_bf16 v[68:71], v[180:183], v[244:247], v[68:71]
	v_mfma_f32_16x16x32_bf16 v[64:67], v[188:191], v[244:247], v[64:67]
	s_setprio 0
	s_barrier
	s_add_i32 s73, s73, s49
	v_lshl_add_u64 v[198:199], s[40:41], 0, v[134:135]
	s_mov_b32 m0, s73
	ds_read_b128 v[192:195], v159 offset:16384
	ds_read_b128 v[206:209], v159 offset:17408
	ds_read_b128 v[210:213], v159 offset:18432
	ds_read_b128 v[214:217], v159 offset:19456
	ds_read_b128 v[218:221], v159 offset:20480
	ds_read_b128 v[222:225], v159 offset:21504
	ds_read_b128 v[240:243], v159 offset:22528
	ds_read_b128 v[244:247], v159 offset:23552
	global_load_lds_dwordx4 v[198:199], off
	s_add_i32 m0, s73, 0x2000
	s_add_u32 s74, s40, 0x40000
	v_lshl_add_u64 v[200:201], s[40:41], 0, v[130:131]
	s_addc_u32 s75, s41, 0
	s_add_i32 s73, s76, s49
	global_load_lds_dwordx4 v[200:201], off
	v_lshl_add_u64 v[202:203], s[74:75], 0, v[134:135]
	s_mov_b32 m0, s73
	v_lshl_add_u64 v[226:227], s[42:43], 0, v[132:133]
	global_load_lds_dwordx4 v[202:203], off
	v_lshl_add_u64 v[202:203], s[74:75], 0, v[130:131]
	s_add_i32 m0, s73, 0x2000
	s_nop 0
	global_load_lds_dwordx4 v[202:203], off
	v_lshl_add_u64 v[202:203], s[42:43], 0, v[136:137]
	s_mov_b32 m0, s51
	s_nop 0
	global_load_lds_dwordx4 v[202:203], off
	s_mov_b32 m0, s52
	s_nop 0
	global_load_lds_dwordx4 v[226:227], off
	s_waitcnt vmcnt(8)
	s_waitcnt lgkmcnt(0)
	s_barrier
	s_setprio 1
	s_waitcnt lgkmcnt(0)
	v_mfma_f32_16x16x32_bf16 v[60:63], v[160:163], v[192:195], v[60:63]
	v_mfma_f32_16x16x32_bf16 v[56:59], v[168:171], v[192:195], v[56:59]
	v_mfma_f32_16x16x32_bf16 v[44:47], v[160:163], v[210:213], v[44:47]
	v_mfma_f32_16x16x32_bf16 v[40:43], v[168:171], v[210:213], v[40:43]
	v_mfma_f32_16x16x32_bf16 v[28:31], v[160:163], v[218:221], v[28:31]
	v_mfma_f32_16x16x32_bf16 v[24:27], v[168:171], v[218:221], v[24:27]
	v_mfma_f32_16x16x32_bf16 v[12:15], v[160:163], v[240:243], v[12:15]
	v_mfma_f32_16x16x32_bf16 v[8:11], v[168:171], v[240:243], v[8:11]
	v_mfma_f32_16x16x32_bf16 v[60:63], v[164:167], v[206:209], v[60:63]
	v_mfma_f32_16x16x32_bf16 v[56:59], v[172:175], v[206:209], v[56:59]
	v_mfma_f32_16x16x32_bf16 v[44:47], v[164:167], v[214:217], v[44:47]
	v_mfma_f32_16x16x32_bf16 v[40:43], v[172:175], v[214:217], v[40:43]
	v_mfma_f32_16x16x32_bf16 v[28:31], v[164:167], v[222:225], v[28:31]
	v_mfma_f32_16x16x32_bf16 v[24:27], v[172:175], v[222:225], v[24:27]
	v_mfma_f32_16x16x32_bf16 v[12:15], v[164:167], v[244:247], v[12:15]
	v_mfma_f32_16x16x32_bf16 v[8:11], v[172:175], v[244:247], v[8:11]
	s_setprio 0
	s_setprio 1
	v_mfma_f32_16x16x32_bf16 v[52:55], v[176:179], v[192:195], v[52:55]
	v_mfma_f32_16x16x32_bf16 v[48:51], v[184:187], v[192:195], v[48:51]
	v_mfma_f32_16x16x32_bf16 v[36:39], v[176:179], v[210:213], v[36:39]
	v_mfma_f32_16x16x32_bf16 v[32:35], v[184:187], v[210:213], v[32:35]
	v_mfma_f32_16x16x32_bf16 v[20:23], v[176:179], v[218:221], v[20:23]
	v_mfma_f32_16x16x32_bf16 v[16:19], v[184:187], v[218:221], v[16:19]
	v_mfma_f32_16x16x32_bf16 v[4:7], v[176:179], v[240:243], v[4:7]
	v_mfma_f32_16x16x32_bf16 v[0:3], v[184:187], v[240:243], v[0:3]
	v_mfma_f32_16x16x32_bf16 v[52:55], v[180:183], v[206:209], v[52:55]
	v_mfma_f32_16x16x32_bf16 v[48:51], v[188:191], v[206:209], v[48:51]
	v_mfma_f32_16x16x32_bf16 v[36:39], v[180:183], v[214:217], v[36:39]
	v_mfma_f32_16x16x32_bf16 v[32:35], v[188:191], v[214:217], v[32:35]
	v_mfma_f32_16x16x32_bf16 v[20:23], v[180:183], v[222:225], v[20:23]
	v_mfma_f32_16x16x32_bf16 v[16:19], v[188:191], v[222:225], v[16:19]
	v_mfma_f32_16x16x32_bf16 v[4:7], v[180:183], v[244:247], v[4:7]
	v_mfma_f32_16x16x32_bf16 v[0:3], v[188:191], v[244:247], v[0:3]
	s_setprio 0
	s_barrier
	s_add_i32 s73, 0, 0x18000
	s_add_i32 s74, 0, 0x1c000
	v_add_u32_e32 v172, s73, v158
	v_add_u32_e32 v188, s74, v158
	ds_read_b128 v[160:163], v172
	ds_read_b128 v[164:167], v172 offset:1024
	ds_read_b128 v[168:171], v172 offset:2048
	ds_read_b128 v[172:175], v172 offset:3072
	ds_read_b128 v[176:179], v188
	ds_read_b128 v[180:183], v188 offset:1024
	ds_read_b128 v[184:187], v188 offset:2048
	ds_read_b128 v[188:191], v188 offset:3072
	s_add_u32 s42, s42, 0x40000
	s_addc_u32 s43, s43, 0
	s_mov_b32 m0, s53
	v_lshl_add_u64 v[248:249], s[42:43], 0, v[136:137]
	ds_read_b128 v[192:195], v159 offset:32768
	ds_read_b128 v[206:209], v159 offset:33792
	ds_read_b128 v[210:213], v159 offset:34816
	ds_read_b128 v[214:217], v159 offset:35840
	ds_read_b128 v[218:221], v159 offset:36864
	ds_read_b128 v[222:225], v159 offset:37888
	ds_read_b128 v[240:243], v159 offset:38912
	ds_read_b128 v[244:247], v159 offset:39936
	global_load_lds_dwordx4 v[248:249], off
	v_lshl_add_u64 v[248:249], s[42:43], 0, v[132:133]
	s_mov_b32 m0, s54
	s_nop 0
	global_load_lds_dwordx4 v[248:249], off
	s_waitcnt vmcnt(8)
	s_waitcnt lgkmcnt(0)
	s_barrier
	s_setprio 1
	s_waitcnt lgkmcnt(0)
	v_mfma_f32_16x16x32_bf16 v[126:129], v[160:163], v[192:195], v[126:129]
	v_mfma_f32_16x16x32_bf16 v[122:125], v[168:171], v[192:195], v[122:125]
	v_mfma_f32_16x16x32_bf16 v[110:113], v[160:163], v[210:213], v[110:113]
	v_mfma_f32_16x16x32_bf16 v[106:109], v[168:171], v[210:213], v[106:109]
	v_mfma_f32_16x16x32_bf16 v[94:97], v[160:163], v[218:221], v[94:97]
	v_mfma_f32_16x16x32_bf16 v[90:93], v[168:171], v[218:221], v[90:93]
	v_mfma_f32_16x16x32_bf16 v[76:79], v[160:163], v[240:243], v[76:79]
	v_mfma_f32_16x16x32_bf16 v[72:75], v[168:171], v[240:243], v[72:75]
	v_mfma_f32_16x16x32_bf16 v[126:129], v[164:167], v[206:209], v[126:129]
	v_mfma_f32_16x16x32_bf16 v[122:125], v[172:175], v[206:209], v[122:125]
	v_mfma_f32_16x16x32_bf16 v[110:113], v[164:167], v[214:217], v[110:113]
	v_mfma_f32_16x16x32_bf16 v[106:109], v[172:175], v[214:217], v[106:109]
	v_mfma_f32_16x16x32_bf16 v[94:97], v[164:167], v[222:225], v[94:97]
	v_mfma_f32_16x16x32_bf16 v[90:93], v[172:175], v[222:225], v[90:93]
	v_mfma_f32_16x16x32_bf16 v[76:79], v[164:167], v[244:247], v[76:79]
	v_mfma_f32_16x16x32_bf16 v[72:75], v[172:175], v[244:247], v[72:75]
	s_setprio 0
	s_setprio 1
	v_mfma_f32_16x16x32_bf16 v[118:121], v[176:179], v[192:195], v[118:121]
	v_mfma_f32_16x16x32_bf16 v[114:117], v[184:187], v[192:195], v[114:117]
	v_mfma_f32_16x16x32_bf16 v[102:105], v[176:179], v[210:213], v[102:105]
	v_mfma_f32_16x16x32_bf16 v[98:101], v[184:187], v[210:213], v[98:101]
	v_mfma_f32_16x16x32_bf16 v[86:89], v[176:179], v[218:221], v[86:89]
	v_mfma_f32_16x16x32_bf16 v[82:85], v[184:187], v[218:221], v[82:85]
	v_mfma_f32_16x16x32_bf16 v[68:71], v[176:179], v[240:243], v[68:71]
	v_mfma_f32_16x16x32_bf16 v[64:67], v[184:187], v[240:243], v[64:67]
	v_mfma_f32_16x16x32_bf16 v[118:121], v[180:183], v[206:209], v[118:121]
	v_mfma_f32_16x16x32_bf16 v[114:117], v[188:191], v[206:209], v[114:117]
	v_mfma_f32_16x16x32_bf16 v[102:105], v[180:183], v[214:217], v[102:105]
	v_mfma_f32_16x16x32_bf16 v[98:101], v[188:191], v[214:217], v[98:101]
	v_mfma_f32_16x16x32_bf16 v[86:89], v[180:183], v[222:225], v[86:89]
	v_mfma_f32_16x16x32_bf16 v[82:85], v[188:191], v[222:225], v[82:85]
	v_mfma_f32_16x16x32_bf16 v[68:71], v[180:183], v[244:247], v[68:71]
	v_mfma_f32_16x16x32_bf16 v[64:67], v[188:191], v[244:247], v[64:67]
	s_setprio 0
	s_barrier
	s_add_i32 s42, s73, s49
	v_lshl_add_u64 v[198:199], v[198:199], 0, s[18:19]
	s_mov_b32 m0, s42
	ds_read_b128 v[192:195], v159 offset:49152
	ds_read_b128 v[206:209], v159 offset:50176
	ds_read_b128 v[210:213], v159 offset:51200
	ds_read_b128 v[214:217], v159 offset:52224
	ds_read_b128 v[218:221], v159 offset:53248
	ds_read_b128 v[222:225], v159 offset:54272
	ds_read_b128 v[240:243], v159 offset:55296
	ds_read_b128 v[244:247], v159 offset:56320
	global_load_lds_dwordx4 v[198:199], off
	s_add_i32 m0, s42, 0x2000
	s_add_u32 s40, s40, 0x40080
	v_lshl_add_u64 v[198:199], v[200:201], 0, s[18:19]
	s_addc_u32 s41, s41, 0
	s_add_i32 s42, s74, s49
	global_load_lds_dwordx4 v[198:199], off
	v_lshl_add_u64 v[198:199], s[40:41], 0, v[134:135]
	s_mov_b32 m0, s42
	s_nop 0
	global_load_lds_dwordx4 v[198:199], off
	v_lshl_add_u64 v[198:199], s[40:41], 0, v[130:131]
	s_add_i32 m0, s42, 0x2000
	s_nop 0
	global_load_lds_dwordx4 v[198:199], off
	v_lshl_add_u64 v[198:199], v[202:203], 0, s[18:19]
	s_mov_b32 m0, s57
	s_nop 0
	global_load_lds_dwordx4 v[198:199], off
	v_lshl_add_u64 v[198:199], v[226:227], 0, s[18:19]
	s_mov_b32 m0, s62
	s_nop 0
	global_load_lds_dwordx4 v[198:199], off
	s_waitcnt vmcnt(8)
	s_waitcnt lgkmcnt(0)
	s_barrier
	s_setprio 1
	s_waitcnt lgkmcnt(0)
	v_mfma_f32_16x16x32_bf16 v[60:63], v[160:163], v[192:195], v[60:63]
	v_mfma_f32_16x16x32_bf16 v[56:59], v[168:171], v[192:195], v[56:59]
	v_mfma_f32_16x16x32_bf16 v[44:47], v[160:163], v[210:213], v[44:47]
	v_mfma_f32_16x16x32_bf16 v[40:43], v[168:171], v[210:213], v[40:43]
	v_mfma_f32_16x16x32_bf16 v[28:31], v[160:163], v[218:221], v[28:31]
	v_mfma_f32_16x16x32_bf16 v[24:27], v[168:171], v[218:221], v[24:27]
	v_mfma_f32_16x16x32_bf16 v[12:15], v[160:163], v[240:243], v[12:15]
	v_mfma_f32_16x16x32_bf16 v[8:11], v[168:171], v[240:243], v[8:11]
	v_mfma_f32_16x16x32_bf16 v[60:63], v[164:167], v[206:209], v[60:63]
	v_mfma_f32_16x16x32_bf16 v[56:59], v[172:175], v[206:209], v[56:59]
	v_mfma_f32_16x16x32_bf16 v[44:47], v[164:167], v[214:217], v[44:47]
	v_mfma_f32_16x16x32_bf16 v[40:43], v[172:175], v[214:217], v[40:43]
	v_mfma_f32_16x16x32_bf16 v[28:31], v[164:167], v[222:225], v[28:31]
	v_mfma_f32_16x16x32_bf16 v[24:27], v[172:175], v[222:225], v[24:27]
	v_mfma_f32_16x16x32_bf16 v[12:15], v[164:167], v[244:247], v[12:15]
	v_mfma_f32_16x16x32_bf16 v[8:11], v[172:175], v[244:247], v[8:11]
	s_setprio 0
	s_setprio 1
	v_mfma_f32_16x16x32_bf16 v[52:55], v[176:179], v[192:195], v[52:55]
	v_mfma_f32_16x16x32_bf16 v[48:51], v[184:187], v[192:195], v[48:51]
	v_mfma_f32_16x16x32_bf16 v[36:39], v[176:179], v[210:213], v[36:39]
	v_mfma_f32_16x16x32_bf16 v[32:35], v[184:187], v[210:213], v[32:35]
	v_mfma_f32_16x16x32_bf16 v[20:23], v[176:179], v[218:221], v[20:23]
	v_mfma_f32_16x16x32_bf16 v[16:19], v[184:187], v[218:221], v[16:19]
	v_mfma_f32_16x16x32_bf16 v[4:7], v[176:179], v[240:243], v[4:7]
	v_mfma_f32_16x16x32_bf16 v[0:3], v[184:187], v[240:243], v[0:3]
	v_mfma_f32_16x16x32_bf16 v[52:55], v[180:183], v[206:209], v[52:55]
	v_mfma_f32_16x16x32_bf16 v[48:51], v[188:191], v[206:209], v[48:51]
	v_mfma_f32_16x16x32_bf16 v[36:39], v[180:183], v[214:217], v[36:39]
	v_mfma_f32_16x16x32_bf16 v[32:35], v[188:191], v[214:217], v[32:35]
	v_mfma_f32_16x16x32_bf16 v[20:23], v[180:183], v[222:225], v[20:23]
	v_mfma_f32_16x16x32_bf16 v[16:19], v[188:191], v[222:225], v[16:19]
	v_mfma_f32_16x16x32_bf16 v[4:7], v[180:183], v[244:247], v[4:7]
	v_mfma_f32_16x16x32_bf16 v[0:3], v[188:191], v[244:247], v[0:3]
	s_setprio 0
	s_add_i32 s72, s72, 2
	s_add_u32 s68, s68, 0x100
	s_addc_u32 s69, s69, 0
	s_add_u32 s38, s38, 0x100
	s_addc_u32 s39, s39, 0
	s_cmp_gt_u32 s72, 13
	s_barrier
	s_cbranch_scc0 .LBB0_651
	s_and_b64 vcc, exec, s[4:5]
	s_cbranch_vccz .LBB0_654
	s_barrier
